# early GEMM epilogue stores the z_b column tiles directly at their parked location; prep's z_b copy sub-phase removed (-50MB traffic per layer)
# speedup vs baseline: 1.0120x; 1.0081x over previous
.LBB0_704:
	s_nop 0
	v_add_co_u32_e32 v0, vcc, 0xfd600000, v88
	s_mov_b32 s3, 0xfe400000
	s_nop 0
	v_addc_co_u32_e32 v1, vcc, -1, v89, vcc
	global_load_dwordx4 v[96:99], v[0:1], off offset:-64
	global_load_dwordx4 v[100:103], v[0:1], off
	global_load_dwordx4 v[30:33], v[80:81], off offset:48
	global_load_dwordx4 v[42:45], v[80:81], off offset:32
	global_load_dwordx4 v[46:49], v[80:81], off offset:16
	global_load_dwordx4 v[50:53], v[80:81], off
	v_add_co_u32_e32 v0, vcc, s3, v88
	s_mov_b32 s3, 0xff200000
	s_nop 0
	v_addc_co_u32_e32 v1, vcc, -1, v89, vcc
	global_load_dwordx4 v[54:57], v[0:1], off offset:-64
	global_load_dwordx4 v[58:61], v[0:1], off
	v_add_u32_e32 v0, 0xffff0000, v92
	v_and_or_b32 v0, v0, s8, v78
	v_lshlrev_b32_e32 v0, 3, v0
	global_load_dwordx4 v[62:65], v0, s[0:1] offset:48
	global_load_dwordx4 v[66:69], v0, s[0:1] offset:32
	global_load_dwordx4 v[70:73], v0, s[0:1] offset:16
	global_load_dwordx4 v[74:77], v0, s[0:1]
	v_add_co_u32_e32 v0, vcc, s3, v88
	v_and_or_b32 v4, v92, s8, v78
	s_nop 0
	v_addc_co_u32_e32 v1, vcc, -1, v89, vcc
	v_lshlrev_b32_e32 v26, 3, v4
	global_load_dwordx4 v[34:37], v[0:1], off offset:-64
	global_load_dwordx4 v[38:41], v[0:1], off
	s_nop 0
	global_load_dwordx4 v[0:3], v[88:89], off offset:-64
	global_load_dwordx4 v[14:17], v[88:89], off
	global_load_dwordx4 v[4:7], v26, s[0:1] offset:48
	global_load_dwordx4 v[18:21], v26, s[0:1] offset:32
	global_load_dwordx4 v[22:25], v26, s[0:1] offset:16
	s_nop 0
	global_load_dwordx4 v[26:29], v26, s[0:1]
	v_add_u32_e32 v108, 0x400, v93
	v_add_u32_e32 v95, 0x800, v93
	v_add_u32_e32 v94, 0xc00, v93
	s_waitcnt vmcnt(18)
	v_lshlrev_b32_e32 v105, 16, v100
	v_lshlrev_b32_e32 v104, 16, v96
	s_waitcnt vmcnt(14)
	v_pk_mul_f32 v[106:107], v[50:51], v[104:105]
	v_pk_mul_f32 v[104:105], v[50:51], v[104:105] op_sel:[1,0] op_sel_hi:[0,1]
	v_add_f32_e32 v110, v104, v105
	v_and_b32_e32 v105, 0xffff0000, v100
	v_and_b32_e32 v104, 0xffff0000, v96
	v_sub_f32_e32 v109, v106, v107
	v_pk_mul_f32 v[106:107], v[52:53], v[104:105]
	v_pk_mul_f32 v[104:105], v[52:53], v[104:105] op_sel:[1,0] op_sel_hi:[0,1]
	v_add_f32_e32 v112, v104, v105
	v_lshlrev_b32_e32 v105, 16, v101
	v_lshlrev_b32_e32 v104, 16, v97
	v_and_b32_e32 v101, 0xffff0000, v101
	v_and_b32_e32 v100, 0xffff0000, v97
	v_sub_f32_e32 v111, v106, v107
	v_pk_mul_f32 v[106:107], v[46:47], v[104:105]
	v_pk_mul_f32 v[104:105], v[46:47], v[104:105] op_sel:[0,1] op_sel_hi:[1,0]
	v_pk_mul_f32 v[96:97], v[48:49], v[100:101]
	v_add_f32_e32 v104, v104, v105
	v_sub_f32_e32 v105, v96, v97
	v_pk_mul_f32 v[96:97], v[48:49], v[100:101] op_sel:[1,0] op_sel_hi:[0,1]
	v_sub_f32_e32 v106, v106, v107
	v_add_f32_e32 v107, v96, v97
	v_lshlrev_b32_e32 v97, 16, v102
	v_lshlrev_b32_e32 v96, 16, v98
	v_pk_mul_f32 v[100:101], v[42:43], v[96:97]
	v_pk_mul_f32 v[96:97], v[42:43], v[96:97] op_sel:[0,1] op_sel_hi:[1,0]
	v_sub_f32_e32 v113, v100, v101
	v_add_f32_e32 v114, v96, v97
	v_and_b32_e32 v97, 0xffff0000, v102
	v_and_b32_e32 v96, 0xffff0000, v98
	v_pk_mul_f32 v[100:101], v[44:45], v[96:97]
	v_pk_mul_f32 v[96:97], v[44:45], v[96:97] op_sel:[1,0] op_sel_hi:[0,1]
	v_add_f32_e32 v115, v96, v97
	v_lshlrev_b32_e32 v97, 16, v103
	v_lshlrev_b32_e32 v96, 16, v99
	v_sub_f32_e32 v102, v100, v101
	v_pk_mul_f32 v[100:101], v[30:31], v[96:97]
	v_pk_mul_f32 v[96:97], v[30:31], v[96:97] op_sel:[0,1] op_sel_hi:[1,0]
	v_sub_f32_e32 v116, v100, v101
	v_add_f32_e32 v117, v96, v97
	v_and_b32_e32 v97, 0xffff0000, v103
	v_and_b32_e32 v96, 0xffff0000, v99
	v_pk_mul_f32 v[98:99], v[32:33], v[96:97]
	v_pk_mul_f32 v[96:97], v[32:33], v[96:97] op_sel:[1,0] op_sel_hi:[0,1]
	v_add_f32_e32 v103, v96, v97
	v_ashrrev_i32_e32 v96, 11, v93
	v_mad_i32_i24 v96, v96, 24, v79
	v_ashrrev_i32_e32 v97, 31, v96
	v_lshlrev_b64 v[96:97], 18, v[96:97]
	v_sub_f32_e32 v99, v98, v99
	v_lshl_add_u64 v[100:101], v[84:85], 0, v[96:97]
	v_cvt_pk_bf16_f32 v96, v109, v111
	v_cvt_pk_bf16_f32 v97, v106, v105
	v_cvt_pk_bf16_f32 v98, v113, v102
	v_cvt_pk_bf16_f32 v99, v116, v99
	global_store_dwordx4 v[100:101], v[96:99], off
	s_add_i32 s2, s2, 4
	s_mov_b64 s[6:7], 0x3800000
	v_cvt_pk_bf16_f32 v96, v110, v112
	v_cvt_pk_bf16_f32 v97, v104, v107
	v_cvt_pk_bf16_f32 v98, v114, v115
	v_cvt_pk_bf16_f32 v99, v117, v103
	global_store_dwordx4 v[100:101], v[96:99], off offset:64
	v_add_u32_e32 v93, 0x1000, v93
	v_add_u32_e32 v92, 0x20000, v92
	s_waitcnt vmcnt(14)
	v_lshlrev_b32_e32 v97, 16, v58
	v_lshlrev_b32_e32 v96, 16, v54
	s_waitcnt vmcnt(10)
	v_pk_mul_f32 v[98:99], v[74:75], v[96:97]
	v_pk_mul_f32 v[74:75], v[74:75], v[96:97] op_sel:[1,0] op_sel_hi:[0,1]
	v_sub_f32_e32 v98, v98, v99
	v_add_f32_e32 v99, v74, v75
	v_and_b32_e32 v75, 0xffff0000, v58
	v_and_b32_e32 v74, 0xffff0000, v54
	v_pk_mul_f32 v[96:97], v[76:77], v[74:75]
	v_pk_mul_f32 v[74:75], v[76:77], v[74:75] op_sel:[1,0] op_sel_hi:[0,1]
	v_sub_f32_e32 v96, v96, v97
	v_add_f32_e32 v97, v74, v75
	v_lshlrev_b32_e32 v75, 16, v59
	v_lshlrev_b32_e32 v74, 16, v55
	v_and_b32_e32 v59, 0xffff0000, v59
	v_and_b32_e32 v58, 0xffff0000, v55
	v_pk_mul_f32 v[76:77], v[70:71], v[74:75]
	v_pk_mul_f32 v[70:71], v[70:71], v[74:75] op_sel:[0,1] op_sel_hi:[1,0]
	v_pk_mul_f32 v[54:55], v[72:73], v[58:59]
	v_add_f32_e32 v70, v70, v71
	v_sub_f32_e32 v71, v54, v55
	v_pk_mul_f32 v[54:55], v[72:73], v[58:59] op_sel:[1,0] op_sel_hi:[0,1]
	v_add_f32_e32 v72, v54, v55
	v_lshlrev_b32_e32 v55, 16, v60
	v_lshlrev_b32_e32 v54, 16, v56
	v_pk_mul_f32 v[58:59], v[66:67], v[54:55]
	v_pk_mul_f32 v[54:55], v[66:67], v[54:55] op_sel:[0,1] op_sel_hi:[1,0]
	v_sub_f32_e32 v73, v58, v59
	v_add_f32_e32 v66, v54, v55
	v_and_b32_e32 v55, 0xffff0000, v60
	v_and_b32_e32 v54, 0xffff0000, v56
	v_pk_mul_f32 v[58:59], v[68:69], v[54:55]
	v_pk_mul_f32 v[54:55], v[68:69], v[54:55] op_sel:[1,0] op_sel_hi:[0,1]
	v_add_f32_e32 v67, v54, v55
	v_lshlrev_b32_e32 v55, 16, v61
	v_lshlrev_b32_e32 v54, 16, v57
	v_sub_f32_e32 v60, v58, v59
	v_pk_mul_f32 v[58:59], v[62:63], v[54:55]
	v_pk_mul_f32 v[54:55], v[62:63], v[54:55] op_sel:[0,1] op_sel_hi:[1,0]
	v_sub_f32_e32 v76, v76, v77
	v_add_f32_e32 v62, v54, v55
	v_and_b32_e32 v55, 0xffff0000, v61
	v_and_b32_e32 v54, 0xffff0000, v57
	v_pk_mul_f32 v[56:57], v[64:65], v[54:55]
	v_pk_mul_f32 v[54:55], v[64:65], v[54:55] op_sel:[1,0] op_sel_hi:[0,1]
	v_add_f32_e32 v61, v54, v55
	v_ashrrev_i32_e32 v54, 11, v108
	v_lshlrev_b32_e32 v55, v90, v108
	v_mad_i32_i24 v54, v54, 24, v79
	v_sub_f32_e32 v57, v56, v57
	v_and_b32_e32 v56, 0x7fe, v55
	v_ashrrev_i32_e32 v55, 31, v54
	v_lshlrev_b64 v[54:55], 18, v[54:55]
	v_lshl_add_u64 v[54:55], s[4:5], 0, v[54:55]
	v_add_lshl_u32 v194, v56, v91, 7
	v_lshl_add_u64 v[54:55], v[54:55], 0, v[194:195]
	v_lshlrev_b32_e32 v194, 1, v78
	v_sub_f32_e32 v68, v58, v59
	v_lshl_add_u64 v[58:59], v[54:55], 0, v[194:195]
	v_cvt_pk_bf16_f32 v54, v98, v96
	v_cvt_pk_bf16_f32 v55, v76, v71
	v_cvt_pk_bf16_f32 v56, v73, v60
	v_cvt_pk_bf16_f32 v57, v68, v57
	global_store_dwordx4 v[58:59], v[54:57], off
	v_lshl_add_u64 v[88:89], v[88:89], 0, s[6:7]
	s_cmp_lt_u32 s2, 12
	v_cvt_pk_bf16_f32 v54, v99, v97
	v_cvt_pk_bf16_f32 v55, v70, v72
	v_cvt_pk_bf16_f32 v56, v66, v67
	v_cvt_pk_bf16_f32 v57, v62, v61
	global_store_dwordx4 v[58:59], v[54:57], off offset:64
	s_waitcnt vmcnt(10)
	s_nop 0
	v_lshlrev_b32_e32 v55, 16, v38
	v_lshlrev_b32_e32 v54, 16, v34
	v_pk_mul_f32 v[56:57], v[50:51], v[54:55]
	v_pk_mul_f32 v[50:51], v[50:51], v[54:55] op_sel:[1,0] op_sel_hi:[0,1]
	v_sub_f32_e32 v56, v56, v57
	v_add_f32_e32 v57, v50, v51
	v_and_b32_e32 v51, 0xffff0000, v38
	v_and_b32_e32 v50, 0xffff0000, v34
	v_pk_mul_f32 v[54:55], v[52:53], v[50:51]
	v_pk_mul_f32 v[50:51], v[52:53], v[50:51] op_sel:[1,0] op_sel_hi:[0,1]
	v_sub_f32_e32 v54, v54, v55
	v_add_f32_e32 v55, v50, v51
	v_lshlrev_b32_e32 v51, 16, v39
	v_lshlrev_b32_e32 v50, 16, v35
	v_and_b32_e32 v39, 0xffff0000, v39
	v_and_b32_e32 v38, 0xffff0000, v35
	v_pk_mul_f32 v[52:53], v[46:47], v[50:51]
	v_pk_mul_f32 v[46:47], v[46:47], v[50:51] op_sel:[1,0] op_sel_hi:[0,1]
	v_pk_mul_f32 v[34:35], v[48:49], v[38:39]
	v_add_f32_e32 v46, v46, v47
	v_sub_f32_e32 v47, v34, v35
	v_pk_mul_f32 v[34:35], v[48:49], v[38:39] op_sel:[1,0] op_sel_hi:[0,1]
	v_add_f32_e32 v48, v34, v35
	v_lshlrev_b32_e32 v35, 16, v40
	v_lshlrev_b32_e32 v34, 16, v36
	v_pk_mul_f32 v[38:39], v[42:43], v[34:35]
	v_pk_mul_f32 v[34:35], v[42:43], v[34:35] op_sel:[1,0] op_sel_hi:[0,1]
	v_add_f32_e32 v42, v34, v35
	v_and_b32_e32 v35, 0xffff0000, v40
	v_and_b32_e32 v34, 0xffff0000, v36
	v_sub_f32_e32 v49, v38, v39
	v_pk_mul_f32 v[38:39], v[44:45], v[34:35]
	v_pk_mul_f32 v[34:35], v[44:45], v[34:35] op_sel:[1,0] op_sel_hi:[0,1]
	v_add_f32_e32 v40, v34, v35
	v_lshlrev_b32_e32 v35, 16, v41
	v_lshlrev_b32_e32 v34, 16, v37
	v_sub_f32_e32 v36, v38, v39
	v_pk_mul_f32 v[38:39], v[30:31], v[34:35]
	v_pk_mul_f32 v[30:31], v[30:31], v[34:35] op_sel:[1,0] op_sel_hi:[0,1]
	v_sub_f32_e32 v38, v38, v39
	v_add_f32_e32 v39, v30, v31
	v_and_b32_e32 v31, 0xffff0000, v41
	v_and_b32_e32 v30, 0xffff0000, v37
	v_pk_mul_f32 v[34:35], v[32:33], v[30:31]
	v_pk_mul_f32 v[30:31], v[32:33], v[30:31] op_sel:[1,0] op_sel_hi:[0,1]
	v_add_f32_e32 v41, v30, v31
	v_ashrrev_i32_e32 v30, 11, v95
	v_mad_i32_i24 v30, v30, 24, v79
	v_ashrrev_i32_e32 v31, 31, v30
	v_lshlrev_b64 v[30:31], 18, v[30:31]
	v_sub_f32_e32 v52, v52, v53
	v_sub_f32_e32 v37, v34, v35
	v_lshl_add_u64 v[34:35], v[84:85], 0, v[30:31]
	v_cvt_pk_bf16_f32 v30, v56, v54
	v_cvt_pk_bf16_f32 v31, v52, v47
	v_cvt_pk_bf16_f32 v32, v49, v36
	v_cvt_pk_bf16_f32 v33, v38, v37
	global_store_dwordx4 v[34:35], v[30:33], off
	s_nop 1
	v_cvt_pk_bf16_f32 v30, v57, v55
	v_cvt_pk_bf16_f32 v31, v46, v48
	v_cvt_pk_bf16_f32 v32, v42, v40
	v_cvt_pk_bf16_f32 v33, v39, v41
	global_store_dwordx4 v[34:35], v[30:33], off offset:64
	s_waitcnt vmcnt(10)
	s_nop 0
	v_lshlrev_b32_e32 v31, 16, v14
	v_lshlrev_b32_e32 v30, 16, v0
	s_waitcnt vmcnt(6)
	v_pk_mul_f32 v[32:33], v[26:27], v[30:31]
	v_pk_mul_f32 v[26:27], v[26:27], v[30:31] op_sel:[1,0] op_sel_hi:[0,1]
	v_sub_f32_e32 v32, v32, v33
	v_add_f32_e32 v33, v26, v27
	v_and_b32_e32 v27, 0xffff0000, v14
	v_and_b32_e32 v26, 0xffff0000, v0
	v_pk_mul_f32 v[30:31], v[28:29], v[26:27]
	v_pk_mul_f32 v[26:27], v[28:29], v[26:27] op_sel:[1,0] op_sel_hi:[0,1]
	v_sub_f32_e32 v30, v30, v31
	v_add_f32_e32 v31, v26, v27
	v_lshlrev_b32_e32 v27, 16, v15
	v_lshlrev_b32_e32 v26, 16, v1
	v_and_b32_e32 v15, 0xffff0000, v15
	v_and_b32_e32 v14, 0xffff0000, v1
	v_pk_mul_f32 v[28:29], v[22:23], v[26:27]
	v_pk_mul_f32 v[22:23], v[22:23], v[26:27] op_sel:[0,1] op_sel_hi:[1,0]
	v_pk_mul_f32 v[0:1], v[24:25], v[14:15]
	v_add_f32_e32 v22, v22, v23
	v_sub_f32_e32 v23, v0, v1
	v_pk_mul_f32 v[0:1], v[24:25], v[14:15] op_sel:[1,0] op_sel_hi:[0,1]
	v_add_f32_e32 v24, v0, v1
	v_lshlrev_b32_e32 v1, 16, v16
	v_lshlrev_b32_e32 v0, 16, v2
	v_pk_mul_f32 v[14:15], v[18:19], v[0:1]
	v_pk_mul_f32 v[0:1], v[18:19], v[0:1] op_sel:[0,1] op_sel_hi:[1,0]
	v_sub_f32_e32 v25, v14, v15
	v_add_f32_e32 v18, v0, v1
	v_and_b32_e32 v1, 0xffff0000, v16
	v_and_b32_e32 v0, 0xffff0000, v2
	v_pk_mul_f32 v[14:15], v[20:21], v[0:1]
	v_pk_mul_f32 v[0:1], v[20:21], v[0:1] op_sel:[1,0] op_sel_hi:[0,1]
	v_add_f32_e32 v19, v0, v1
	v_lshlrev_b32_e32 v1, 16, v17
	v_lshlrev_b32_e32 v0, 16, v3
	v_sub_f32_e32 v16, v14, v15
	v_pk_mul_f32 v[14:15], v[4:5], v[0:1]
	v_pk_mul_f32 v[0:1], v[4:5], v[0:1] op_sel:[0,1] op_sel_hi:[1,0]
	v_sub_f32_e32 v14, v14, v15
	v_add_f32_e32 v15, v0, v1
	v_and_b32_e32 v1, 0xffff0000, v17
	v_and_b32_e32 v0, 0xffff0000, v3
	v_pk_mul_f32 v[2:3], v[6:7], v[0:1]
	v_pk_mul_f32 v[0:1], v[6:7], v[0:1] op_sel:[1,0] op_sel_hi:[0,1]
	v_add_f32_e32 v6, v0, v1
	v_ashrrev_i32_e32 v0, 11, v94
	v_lshlrev_b32_e32 v1, v90, v94
	v_mad_i32_i24 v0, v0, 24, v79
	v_sub_f32_e32 v17, v2, v3
	v_and_b32_e32 v2, 0x7fe, v1
	v_ashrrev_i32_e32 v1, 31, v0
	v_lshlrev_b64 v[0:1], 18, v[0:1]
	v_lshl_add_u64 v[0:1], s[4:5], 0, v[0:1]
	v_add_lshl_u32 v2, v2, v91, 7
	v_mov_b32_e32 v3, v195
	v_lshl_add_u64 v[0:1], v[0:1], 0, v[2:3]
	v_sub_f32_e32 v28, v28, v29
	v_lshl_add_u64 v[4:5], v[0:1], 0, v[194:195]
	v_cvt_pk_bf16_f32 v0, v32, v30
	v_cvt_pk_bf16_f32 v1, v28, v23
	v_cvt_pk_bf16_f32 v2, v25, v16
	v_cvt_pk_bf16_f32 v3, v14, v17
	global_store_dwordx4 v[4:5], v[0:3], off
	s_nop 1
	v_cvt_pk_bf16_f32 v0, v33, v31
	v_cvt_pk_bf16_f32 v1, v22, v24
	v_cvt_pk_bf16_f32 v2, v18, v19
	v_cvt_pk_bf16_f32 v3, v15, v6
	global_store_dwordx4 v[4:5], v[0:3], off offset:64
	s_cbranch_scc1 .LBB0_704
	s_mov_b32 s65, 0x800000
	s_mov_b64 s[66:67], 0x3fffff
	s_movk_i32 s2, 0x3000
	s_movk_i32 s3, 0x3800

.LBB0_724:
	s_add_u32 s2, s42, 0xfffc0080
	s_addc_u32 s3, s43, -1
	s_add_i32 s24, 0, 0x10000
	v_add_u32_e32 v126, s24, v163
	ds_read_b128 v[110:113], v126
	ds_read_b128 v[114:117], v126 offset:1024
	ds_read_b128 v[118:121], v126 offset:2048
	ds_read_b128 v[126:129], v126 offset:3072
	s_cmp_eq_u32 s57, 12
	s_cselect_b32 s45, s11, s3
	s_cselect_b32 s44, s53, s2
	s_cselect_b32 s3, s9, s56
	s_cselect_b32 s2, s54, s55
	v_lshl_add_u64 v[200:201], s[42:43], 0, v[154:155]
	s_add_i32 m0, s41, 0xc000
	ds_read_b128 v[158:161], v165
	ds_read_b128 v[166:169], v165 offset:1024
	ds_read_b128 v[170:173], v165 offset:2048
	ds_read_b128 v[174:177], v165 offset:3072
	ds_read_b128 v[178:181], v165 offset:4096
	ds_read_b128 v[182:185], v165 offset:5120
	ds_read_b128 v[186:189], v165 offset:6144
	ds_read_b128 v[190:193], v165 offset:7168
	global_load_lds_dwordx4 v[200:201], off
	v_lshl_add_u64 v[200:201], s[42:43], 0, v[156:157]
	s_add_i32 m0, s41, 0xe000
	s_nop 0
	global_load_lds_dwordx4 v[200:201], off
	s_waitcnt lgkmcnt(8)
	s_barrier
	s_waitcnt lgkmcnt(0)
	s_setprio 1
	s_waitcnt lgkmcnt(0)
	v_mfma_f32_16x16x32_bf16 v[146:149], v[110:113], v[158:161], v[146:149]
	v_mfma_f32_16x16x32_bf16 v[142:145], v[118:121], v[158:161], v[142:145]
	v_mfma_f32_16x16x32_bf16 v[130:133], v[110:113], v[170:173], v[130:133]
	v_mfma_f32_16x16x32_bf16 v[122:125], v[118:121], v[170:173], v[122:125]
	v_mfma_f32_16x16x32_bf16 v[98:101], v[110:113], v[178:181], v[98:101]
	v_mfma_f32_16x16x32_bf16 v[94:97], v[118:121], v[178:181], v[94:97]
	v_mfma_f32_16x16x32_bf16 v[82:85], v[110:113], v[186:189], v[82:85]
	v_mfma_f32_16x16x32_bf16 v[78:81], v[118:121], v[186:189], v[78:81]
	v_mfma_f32_16x16x32_bf16 v[146:149], v[114:117], v[166:169], v[146:149]
	v_mfma_f32_16x16x32_bf16 v[142:145], v[126:129], v[166:169], v[142:145]
	v_mfma_f32_16x16x32_bf16 v[130:133], v[114:117], v[174:177], v[130:133]
	v_mfma_f32_16x16x32_bf16 v[122:125], v[126:129], v[174:177], v[122:125]
	v_mfma_f32_16x16x32_bf16 v[98:101], v[114:117], v[182:185], v[98:101]
	v_mfma_f32_16x16x32_bf16 v[94:97], v[126:129], v[182:185], v[94:97]
	v_mfma_f32_16x16x32_bf16 v[82:85], v[114:117], v[190:193], v[82:85]
	v_mfma_f32_16x16x32_bf16 v[78:81], v[126:129], v[190:193], v[78:81]
	s_setprio 0
	s_barrier
	s_add_i32 s25, 0, 0x14000
	s_add_i32 s24, s24, s26
	v_add_u32_e32 v196, s25, v163
	v_lshl_add_u64 v[216:217], s[2:3], 0, v[194:195]
	s_mov_b32 m0, s24
	ds_read_b128 v[200:203], v196
	ds_read_b128 v[204:207], v196 offset:1024
	ds_read_b128 v[208:211], v196 offset:2048
	ds_read_b128 v[212:215], v196 offset:3072
	global_load_lds_dwordx4 v[216:217], off
	v_lshl_add_u64 v[218:219], s[2:3], 0, v[8:9]
	s_add_i32 m0, s24, 0x2000
	s_nop 0
	global_load_lds_dwordx4 v[218:219], off
	s_barrier
	s_waitcnt lgkmcnt(0)
	s_setprio 1
	s_waitcnt lgkmcnt(0)
	v_mfma_f32_16x16x32_bf16 v[138:141], v[200:203], v[158:161], v[138:141]
	v_mfma_f32_16x16x32_bf16 v[134:137], v[208:211], v[158:161], v[134:137]
	v_mfma_f32_16x16x32_bf16 v[106:109], v[200:203], v[170:173], v[106:109]
	v_mfma_f32_16x16x32_bf16 v[102:105], v[208:211], v[170:173], v[102:105]
	v_mfma_f32_16x16x32_bf16 v[90:93], v[200:203], v[178:181], v[90:93]
	v_mfma_f32_16x16x32_bf16 v[86:89], v[208:211], v[178:181], v[86:89]
	v_mfma_f32_16x16x32_bf16 v[74:77], v[200:203], v[186:189], v[74:77]
	v_mfma_f32_16x16x32_bf16 v[70:73], v[208:211], v[186:189], v[70:73]
	v_mfma_f32_16x16x32_bf16 v[138:141], v[204:207], v[166:169], v[138:141]
	v_mfma_f32_16x16x32_bf16 v[134:137], v[212:215], v[166:169], v[134:137]
	v_mfma_f32_16x16x32_bf16 v[106:109], v[204:207], v[174:177], v[106:109]
	v_mfma_f32_16x16x32_bf16 v[102:105], v[212:215], v[174:177], v[102:105]
	v_mfma_f32_16x16x32_bf16 v[90:93], v[204:207], v[182:185], v[90:93]
	v_mfma_f32_16x16x32_bf16 v[86:89], v[212:215], v[182:185], v[86:89]
	v_mfma_f32_16x16x32_bf16 v[74:77], v[204:207], v[190:193], v[74:77]
	v_mfma_f32_16x16x32_bf16 v[70:73], v[212:215], v[190:193], v[70:73]
	s_setprio 0
	s_mov_b32 m0, s41
	v_lshl_add_u64 v[228:229], s[44:45], 0, v[152:153]
	s_barrier
	ds_read_b128 v[158:161], v165 offset:16384
	ds_read_b128 v[166:169], v165 offset:17408
	ds_read_b128 v[170:173], v165 offset:18432
	ds_read_b128 v[174:177], v165 offset:19456
	ds_read_b128 v[178:181], v165 offset:20480
	ds_read_b128 v[182:185], v165 offset:21504
	ds_read_b128 v[186:189], v165 offset:22528
	ds_read_b128 v[190:193], v165 offset:23552
	global_load_lds_dwordx4 v[228:229], off
	v_lshl_add_u64 v[230:231], s[44:45], 0, v[150:151]
	s_mov_b32 m0, s46
	s_nop 0
	global_load_lds_dwordx4 v[230:231], off
	s_barrier
	s_waitcnt lgkmcnt(0)
	s_setprio 1
	s_waitcnt lgkmcnt(0)
	v_mfma_f32_16x16x32_bf16 v[66:69], v[110:113], v[158:161], v[66:69]
	v_mfma_f32_16x16x32_bf16 v[62:65], v[118:121], v[158:161], v[62:65]
	v_mfma_f32_16x16x32_bf16 v[54:57], v[110:113], v[170:173], v[54:57]
	v_mfma_f32_16x16x32_bf16 v[46:49], v[118:121], v[170:173], v[46:49]
	v_mfma_f32_16x16x32_bf16 v[38:41], v[110:113], v[178:181], v[38:41]
	v_mfma_f32_16x16x32_bf16 v[30:33], v[118:121], v[178:181], v[30:33]
	v_mfma_f32_16x16x32_bf16 v[22:25], v[110:113], v[186:189], v[22:25]
	v_mfma_f32_16x16x32_bf16 v[14:17], v[118:121], v[186:189], v[14:17]
	v_mfma_f32_16x16x32_bf16 v[66:69], v[114:117], v[166:169], v[66:69]
	v_mfma_f32_16x16x32_bf16 v[62:65], v[126:129], v[166:169], v[62:65]
	v_mfma_f32_16x16x32_bf16 v[54:57], v[114:117], v[174:177], v[54:57]
	v_mfma_f32_16x16x32_bf16 v[46:49], v[126:129], v[174:177], v[46:49]
	v_mfma_f32_16x16x32_bf16 v[38:41], v[114:117], v[182:185], v[38:41]
	v_mfma_f32_16x16x32_bf16 v[30:33], v[126:129], v[182:185], v[30:33]
	v_mfma_f32_16x16x32_bf16 v[22:25], v[114:117], v[190:193], v[22:25]
	v_mfma_f32_16x16x32_bf16 v[14:17], v[126:129], v[190:193], v[14:17]
	s_setprio 0
	s_barrier
	s_add_u32 s58, s2, 0x40000
	s_addc_u32 s59, s3, 0
	s_add_i32 s24, s25, s26
	v_lshl_add_u64 v[110:111], s[58:59], 0, v[194:195]
	s_mov_b32 m0, s24
	s_nop 0
	global_load_lds_dwordx4 v[110:111], off
	v_lshl_add_u64 v[110:111], s[58:59], 0, v[8:9]
	s_add_i32 m0, s24, 0x2000
	s_nop 0
	global_load_lds_dwordx4 v[110:111], off
	s_waitcnt vmcnt(6)
	s_barrier
	s_setprio 1
	v_mfma_f32_16x16x32_bf16 v[58:61], v[200:203], v[158:161], v[58:61]
	v_mfma_f32_16x16x32_bf16 v[50:53], v[208:211], v[158:161], v[50:53]
	v_mfma_f32_16x16x32_bf16 v[42:45], v[200:203], v[170:173], v[42:45]
	v_mfma_f32_16x16x32_bf16 v[34:37], v[208:211], v[170:173], v[34:37]
	v_mfma_f32_16x16x32_bf16 v[26:29], v[200:203], v[178:181], v[26:29]
	v_mfma_f32_16x16x32_bf16 v[18:21], v[208:211], v[178:181], v[18:21]
	v_mfma_f32_16x16x32_bf16 v[4:7], v[200:203], v[186:189], v[4:7]
	v_mfma_f32_16x16x32_bf16 v[0:3], v[208:211], v[186:189], v[0:3]
	v_mfma_f32_16x16x32_bf16 v[58:61], v[204:207], v[166:169], v[58:61]
	v_mfma_f32_16x16x32_bf16 v[50:53], v[212:215], v[166:169], v[50:53]
	v_mfma_f32_16x16x32_bf16 v[42:45], v[204:207], v[174:177], v[42:45]
	v_mfma_f32_16x16x32_bf16 v[34:37], v[212:215], v[174:177], v[34:37]
	v_mfma_f32_16x16x32_bf16 v[26:29], v[204:207], v[182:185], v[26:29]
	v_mfma_f32_16x16x32_bf16 v[18:21], v[212:215], v[182:185], v[18:21]
	v_mfma_f32_16x16x32_bf16 v[4:7], v[204:207], v[190:193], v[4:7]
	v_mfma_f32_16x16x32_bf16 v[0:3], v[212:215], v[190:193], v[0:3]
	s_setprio 0
	s_add_i32 s24, 0, 0x18000
	v_add_u32_e32 v126, s24, v163
	s_barrier
	ds_read_b128 v[110:113], v126
	ds_read_b128 v[114:117], v126 offset:1024
	ds_read_b128 v[118:121], v126 offset:2048
	ds_read_b128 v[126:129], v126 offset:3072
	s_add_u32 s44, s44, 0x40000
	s_addc_u32 s45, s45, 0
	s_mov_b32 m0, s47
	v_lshl_add_u64 v[200:201], s[44:45], 0, v[152:153]
	ds_read_b128 v[158:161], v165 offset:32768
	ds_read_b128 v[166:169], v165 offset:33792
	ds_read_b128 v[170:173], v165 offset:34816
	ds_read_b128 v[174:177], v165 offset:35840
	ds_read_b128 v[178:181], v165 offset:36864
	ds_read_b128 v[182:185], v165 offset:37888
	ds_read_b128 v[186:189], v165 offset:38912
	ds_read_b128 v[190:193], v165 offset:39936
	global_load_lds_dwordx4 v[200:201], off
	v_lshl_add_u64 v[200:201], s[44:45], 0, v[150:151]
	s_mov_b32 m0, s48
	s_nop 0
	global_load_lds_dwordx4 v[200:201], off
	s_waitcnt lgkmcnt(8)
	s_barrier
	s_waitcnt lgkmcnt(0)
	s_setprio 1
	s_waitcnt lgkmcnt(0)
	v_mfma_f32_16x16x32_bf16 v[146:149], v[110:113], v[158:161], v[146:149]
	v_mfma_f32_16x16x32_bf16 v[142:145], v[118:121], v[158:161], v[142:145]
	v_mfma_f32_16x16x32_bf16 v[130:133], v[110:113], v[170:173], v[130:133]
	v_mfma_f32_16x16x32_bf16 v[122:125], v[118:121], v[170:173], v[122:125]
	v_mfma_f32_16x16x32_bf16 v[98:101], v[110:113], v[178:181], v[98:101]
	v_mfma_f32_16x16x32_bf16 v[94:97], v[118:121], v[178:181], v[94:97]
	v_mfma_f32_16x16x32_bf16 v[82:85], v[110:113], v[186:189], v[82:85]
	v_mfma_f32_16x16x32_bf16 v[78:81], v[118:121], v[186:189], v[78:81]
	v_mfma_f32_16x16x32_bf16 v[146:149], v[114:117], v[166:169], v[146:149]
	v_mfma_f32_16x16x32_bf16 v[142:145], v[126:129], v[166:169], v[142:145]
	v_mfma_f32_16x16x32_bf16 v[130:133], v[114:117], v[174:177], v[130:133]
	v_mfma_f32_16x16x32_bf16 v[122:125], v[126:129], v[174:177], v[122:125]
	v_mfma_f32_16x16x32_bf16 v[98:101], v[114:117], v[182:185], v[98:101]
	v_mfma_f32_16x16x32_bf16 v[94:97], v[126:129], v[182:185], v[94:97]
	v_mfma_f32_16x16x32_bf16 v[82:85], v[114:117], v[190:193], v[82:85]
	v_mfma_f32_16x16x32_bf16 v[78:81], v[126:129], v[190:193], v[78:81]
	s_setprio 0
	s_barrier
	s_add_i32 s25, 0, 0x1c000
	s_add_i32 s24, s24, s26
	v_add_u32_e32 v196, s25, v163
	v_lshl_add_u64 v[216:217], v[216:217], 0, s[22:23]
	s_mov_b32 m0, s24
	ds_read_b128 v[200:203], v196
	ds_read_b128 v[204:207], v196 offset:1024
	ds_read_b128 v[208:211], v196 offset:2048
	ds_read_b128 v[212:215], v196 offset:3072
	global_load_lds_dwordx4 v[216:217], off
	v_lshl_add_u64 v[216:217], v[218:219], 0, s[22:23]
	s_add_i32 m0, s24, 0x2000
	s_nop 0
	global_load_lds_dwordx4 v[216:217], off
	s_barrier
	s_waitcnt lgkmcnt(0)
	s_setprio 1
	s_waitcnt lgkmcnt(0)
	v_mfma_f32_16x16x32_bf16 v[138:141], v[200:203], v[158:161], v[138:141]
	v_mfma_f32_16x16x32_bf16 v[134:137], v[208:211], v[158:161], v[134:137]
	v_mfma_f32_16x16x32_bf16 v[106:109], v[200:203], v[170:173], v[106:109]
	v_mfma_f32_16x16x32_bf16 v[102:105], v[208:211], v[170:173], v[102:105]
	v_mfma_f32_16x16x32_bf16 v[90:93], v[200:203], v[178:181], v[90:93]
	v_mfma_f32_16x16x32_bf16 v[86:89], v[208:211], v[178:181], v[86:89]
	v_mfma_f32_16x16x32_bf16 v[74:77], v[200:203], v[186:189], v[74:77]
	v_mfma_f32_16x16x32_bf16 v[70:73], v[208:211], v[186:189], v[70:73]
	v_mfma_f32_16x16x32_bf16 v[138:141], v[204:207], v[166:169], v[138:141]
	v_mfma_f32_16x16x32_bf16 v[134:137], v[212:215], v[166:169], v[134:137]
	v_mfma_f32_16x16x32_bf16 v[106:109], v[204:207], v[174:177], v[106:109]
	v_mfma_f32_16x16x32_bf16 v[102:105], v[212:215], v[174:177], v[102:105]
	v_mfma_f32_16x16x32_bf16 v[90:93], v[204:207], v[182:185], v[90:93]
	v_mfma_f32_16x16x32_bf16 v[86:89], v[212:215], v[182:185], v[86:89]
	v_mfma_f32_16x16x32_bf16 v[74:77], v[204:207], v[190:193], v[74:77]
	v_mfma_f32_16x16x32_bf16 v[70:73], v[212:215], v[190:193], v[70:73]
	s_setprio 0
	s_mov_b32 m0, s49
	v_lshl_add_u64 v[216:217], v[228:229], 0, s[22:23]
	s_barrier
	ds_read_b128 v[158:161], v165 offset:49152
	ds_read_b128 v[166:169], v165 offset:50176
	ds_read_b128 v[170:173], v165 offset:51200
	ds_read_b128 v[174:177], v165 offset:52224
	ds_read_b128 v[178:181], v165 offset:53248
	ds_read_b128 v[182:185], v165 offset:54272
	ds_read_b128 v[186:189], v165 offset:55296
	ds_read_b128 v[190:193], v165 offset:56320
	global_load_lds_dwordx4 v[216:217], off
	v_lshl_add_u64 v[216:217], v[230:231], 0, s[22:23]
	s_mov_b32 m0, s50
	s_nop 0
	global_load_lds_dwordx4 v[216:217], off
	s_barrier
	s_waitcnt lgkmcnt(0)
	s_setprio 1
	s_waitcnt lgkmcnt(0)
	v_mfma_f32_16x16x32_bf16 v[66:69], v[110:113], v[158:161], v[66:69]
	v_mfma_f32_16x16x32_bf16 v[62:65], v[118:121], v[158:161], v[62:65]
	v_mfma_f32_16x16x32_bf16 v[54:57], v[110:113], v[170:173], v[54:57]
	v_mfma_f32_16x16x32_bf16 v[46:49], v[118:121], v[170:173], v[46:49]
	v_mfma_f32_16x16x32_bf16 v[38:41], v[110:113], v[178:181], v[38:41]
	v_mfma_f32_16x16x32_bf16 v[30:33], v[118:121], v[178:181], v[30:33]
	v_mfma_f32_16x16x32_bf16 v[22:25], v[110:113], v[186:189], v[22:25]
	v_mfma_f32_16x16x32_bf16 v[14:17], v[118:121], v[186:189], v[14:17]
	v_mfma_f32_16x16x32_bf16 v[66:69], v[114:117], v[166:169], v[66:69]
	v_mfma_f32_16x16x32_bf16 v[62:65], v[126:129], v[166:169], v[62:65]
	v_mfma_f32_16x16x32_bf16 v[54:57], v[114:117], v[174:177], v[54:57]
	v_mfma_f32_16x16x32_bf16 v[46:49], v[126:129], v[174:177], v[46:49]
	v_mfma_f32_16x16x32_bf16 v[38:41], v[114:117], v[182:185], v[38:41]
	v_mfma_f32_16x16x32_bf16 v[30:33], v[126:129], v[182:185], v[30:33]
	v_mfma_f32_16x16x32_bf16 v[22:25], v[114:117], v[190:193], v[22:25]
	v_mfma_f32_16x16x32_bf16 v[14:17], v[126:129], v[190:193], v[14:17]
	s_setprio 0
	s_barrier
	s_add_u32 s2, s2, 0x40080
	s_addc_u32 s3, s3, 0
	s_add_i32 s24, s25, s26
	v_lshl_add_u64 v[110:111], s[2:3], 0, v[194:195]
	s_mov_b32 m0, s24
	s_nop 0
	global_load_lds_dwordx4 v[110:111], off
	v_lshl_add_u64 v[110:111], s[2:3], 0, v[8:9]
	s_add_i32 m0, s24, 0x2000
	s_nop 0
	global_load_lds_dwordx4 v[110:111], off
	s_waitcnt vmcnt(6)
	s_barrier
	s_setprio 1
	v_mfma_f32_16x16x32_bf16 v[58:61], v[200:203], v[158:161], v[58:61]
	v_mfma_f32_16x16x32_bf16 v[50:53], v[208:211], v[158:161], v[50:53]
	v_mfma_f32_16x16x32_bf16 v[42:45], v[200:203], v[170:173], v[42:45]
	v_mfma_f32_16x16x32_bf16 v[34:37], v[208:211], v[170:173], v[34:37]
	v_mfma_f32_16x16x32_bf16 v[26:29], v[200:203], v[178:181], v[26:29]
	v_mfma_f32_16x16x32_bf16 v[18:21], v[208:211], v[178:181], v[18:21]
	v_mfma_f32_16x16x32_bf16 v[4:7], v[200:203], v[186:189], v[4:7]
	v_mfma_f32_16x16x32_bf16 v[0:3], v[208:211], v[186:189], v[0:3]
	v_mfma_f32_16x16x32_bf16 v[58:61], v[204:207], v[166:169], v[58:61]
	v_mfma_f32_16x16x32_bf16 v[50:53], v[212:215], v[166:169], v[50:53]
	v_mfma_f32_16x16x32_bf16 v[42:45], v[204:207], v[174:177], v[42:45]
	v_mfma_f32_16x16x32_bf16 v[34:37], v[212:215], v[174:177], v[34:37]
	v_mfma_f32_16x16x32_bf16 v[26:29], v[204:207], v[182:185], v[26:29]
	v_mfma_f32_16x16x32_bf16 v[18:21], v[212:215], v[182:185], v[18:21]
	v_mfma_f32_16x16x32_bf16 v[4:7], v[204:207], v[190:193], v[4:7]
	v_mfma_f32_16x16x32_bf16 v[0:3], v[212:215], v[190:193], v[0:3]
	s_setprio 0
	s_add_i32 s57, s57, 2
	s_add_u32 s42, s42, 0x100
	s_addc_u32 s43, s43, 0
	s_add_u32 s55, s55, 0x100
	s_addc_u32 s56, s56, 0
	s_cmp_gt_u32 s57, 13
	s_barrier
	s_cbranch_scc0 .LBB0_724
	v_lshl_or_b32 v160, s52, 8, v164
	v_ashrrev_i32_e32 v161, 31, v160
	v_lshl_add_u64 v[114:115], v[160:161], 2, s[6:7]
	global_load_dwordx4 v[118:121], v[114:115], off offset:16
	global_load_dwordx4 v[126:129], v[114:115], off
	global_load_dwordx4 v[110:113], v[114:115], off offset:528
	s_nop 0
	global_load_dwordx4 v[114:117], v[114:115], off offset:512
	v_lshl_add_u32 v166, s40, 8, v162
	v_mov_b64_e32 v[158:159], s[0:1]
	s_movk_i32 s9, 0x3800
	v_lshlrev_b64 v[160:161], 1, v[160:161]
	s_cmp_lt_u32 s52, 25
	s_cbranch_scc1 .Lzb_skip
	s_movk_i32 s9, 0x1000
	s_add_u32 s98, s38, 0x259eb400
	s_addc_u32 s99, s39, 0
	v_mov_b64_e32 v[158:159], s[98:99]
	s_mov_b32 s98, 0xffffce00
	s_mov_b32 s99, -1
	v_lshl_add_u64 v[160:161], v[160:161], 0, s[98:99]
.Lzb_skip:
	v_mad_i64_i32 v[168:169], s[2:3], v166, s9, v[158:159]
	v_lshl_add_u64 v[168:169], v[168:169], 0, v[160:161]
	s_and_b64 vcc, exec, s[4:5]
	s_mov_b32 s52, s8
	s_mov_b32 s40, s10
	s_mov_b64 s[42:43], s[12:13]
	s_waitcnt vmcnt(0)
	v_pk_add_f32 v[170:171], v[144:145], v[120:121]
	v_pk_add_f32 v[148:149], v[148:149], v[128:129]
	v_pk_add_f32 v[146:147], v[146:147], v[126:127]
	v_pk_add_f32 v[144:145], v[142:143], v[118:119]
	v_cvt_pk_bf16_f32 v142, v146, v147
	v_cvt_pk_bf16_f32 v143, v148, v149
	v_pk_add_f32 v[138:139], v[138:139], v[114:115]
	v_cvt_pk_bf16_f32 v144, v144, v145
	v_cvt_pk_bf16_f32 v145, v170, v171
	global_store_dwordx4 v[168:169], v[142:145], off
	v_pk_add_f32 v[140:141], v[140:141], v[116:117]
	v_pk_add_f32 v[132:133], v[132:133], v[128:129]
	v_pk_add_f32 v[142:143], v[136:137], v[112:113]
	v_pk_add_f32 v[136:137], v[134:135], v[110:111]
	v_cvt_pk_bf16_f32 v134, v138, v139
	v_cvt_pk_bf16_f32 v135, v140, v141
	v_pk_add_f32 v[130:131], v[130:131], v[126:127]
	v_cvt_pk_bf16_f32 v136, v136, v137
	v_cvt_pk_bf16_f32 v137, v142, v143
	global_store_dwordx4 v[168:169], v[134:137], off offset:256
	v_pk_add_f32 v[106:107], v[106:107], v[114:115]
	v_pk_add_f32 v[108:109], v[108:109], v[116:117]
	v_or_b32_e32 v134, 16, v166
	v_mad_i64_i32 v[134:135], s[2:3], v134, s9, v[158:159]
	v_lshl_add_u64 v[134:135], v[134:135], 0, v[160:161]
	v_pk_add_f32 v[136:137], v[124:125], v[120:121]
	v_pk_add_f32 v[124:125], v[122:123], v[118:119]
	v_cvt_pk_bf16_f32 v122, v130, v131
	v_cvt_pk_bf16_f32 v123, v132, v133
	v_pk_add_f32 v[100:101], v[100:101], v[128:129]
	v_cvt_pk_bf16_f32 v124, v124, v125
	v_cvt_pk_bf16_f32 v125, v136, v137
	global_store_dwordx4 v[134:135], v[122:125], off
	v_pk_add_f32 v[98:99], v[98:99], v[126:127]
	v_pk_add_f32 v[90:91], v[90:91], v[114:115]
	v_pk_add_f32 v[122:123], v[104:105], v[112:113]
	v_pk_add_f32 v[104:105], v[102:103], v[110:111]
	v_cvt_pk_bf16_f32 v102, v106, v107
	v_cvt_pk_bf16_f32 v103, v108, v109
	v_pk_add_f32 v[92:93], v[92:93], v[116:117]
	v_cvt_pk_bf16_f32 v104, v104, v105
	v_cvt_pk_bf16_f32 v105, v122, v123
	global_store_dwordx4 v[134:135], v[102:105], off offset:256
	v_pk_add_f32 v[84:85], v[84:85], v[128:129]
	v_pk_add_f32 v[82:83], v[82:83], v[126:127]
	v_or_b32_e32 v102, 32, v166
	v_mad_i64_i32 v[102:103], s[2:3], v102, s9, v[158:159]
	v_lshl_add_u64 v[102:103], v[102:103], 0, v[160:161]
	v_pk_add_f32 v[104:105], v[96:97], v[120:121]
	v_pk_add_f32 v[96:97], v[94:95], v[118:119]
	v_cvt_pk_bf16_f32 v94, v98, v99
	v_cvt_pk_bf16_f32 v95, v100, v101
	v_pk_add_f32 v[74:75], v[74:75], v[114:115]
	v_cvt_pk_bf16_f32 v96, v96, v97
	v_cvt_pk_bf16_f32 v97, v104, v105
	global_store_dwordx4 v[102:103], v[94:97], off
	v_pk_add_f32 v[76:77], v[76:77], v[116:117]
	v_pk_add_f32 v[68:69], v[68:69], v[128:129]
	v_pk_add_f32 v[94:95], v[88:89], v[112:113]
	v_pk_add_f32 v[88:89], v[86:87], v[110:111]
	v_cvt_pk_bf16_f32 v86, v90, v91
	v_cvt_pk_bf16_f32 v87, v92, v93
	v_pk_add_f32 v[66:67], v[66:67], v[126:127]
	v_cvt_pk_bf16_f32 v88, v88, v89
	v_cvt_pk_bf16_f32 v89, v94, v95
	global_store_dwordx4 v[102:103], v[86:89], off offset:256
	v_pk_add_f32 v[58:59], v[58:59], v[114:115]
	v_pk_add_f32 v[60:61], v[60:61], v[116:117]
	v_or_b32_e32 v86, 48, v166
	v_mad_i64_i32 v[86:87], s[2:3], v86, s9, v[158:159]
	v_lshl_add_u64 v[86:87], v[86:87], 0, v[160:161]
	v_pk_add_f32 v[88:89], v[80:81], v[120:121]
	v_pk_add_f32 v[80:81], v[78:79], v[118:119]
	v_cvt_pk_bf16_f32 v78, v82, v83
	v_cvt_pk_bf16_f32 v79, v84, v85
	v_pk_add_f32 v[54:55], v[54:55], v[126:127]
	v_cvt_pk_bf16_f32 v80, v80, v81
	v_cvt_pk_bf16_f32 v81, v88, v89
	global_store_dwordx4 v[86:87], v[78:81], off
	v_pk_add_f32 v[42:43], v[42:43], v[114:115]
	v_pk_add_f32 v[44:45], v[44:45], v[116:117]
	v_pk_add_f32 v[78:79], v[72:73], v[112:113]
	v_pk_add_f32 v[72:73], v[70:71], v[110:111]
	v_cvt_pk_bf16_f32 v70, v74, v75
	v_cvt_pk_bf16_f32 v71, v76, v77
	v_pk_add_f32 v[38:39], v[38:39], v[126:127]
	v_cvt_pk_bf16_f32 v72, v72, v73
	v_cvt_pk_bf16_f32 v73, v78, v79
	global_store_dwordx4 v[86:87], v[70:73], off offset:256
	v_pk_add_f32 v[26:27], v[26:27], v[114:115]
	v_pk_add_f32 v[28:29], v[28:29], v[116:117]
	v_add_u32_e32 v70, 0x80, v166
	v_mad_i64_i32 v[70:71], s[2:3], v70, s9, v[158:159]
	v_lshl_add_u64 v[70:71], v[70:71], 0, v[160:161]
	v_pk_add_f32 v[72:73], v[64:65], v[120:121]
	v_pk_add_f32 v[64:65], v[62:63], v[118:119]
	v_cvt_pk_bf16_f32 v62, v66, v67
	v_cvt_pk_bf16_f32 v63, v68, v69
	v_pk_add_f32 v[22:23], v[22:23], v[126:127]
	v_cvt_pk_bf16_f32 v64, v64, v65
	v_cvt_pk_bf16_f32 v65, v72, v73
	global_store_dwordx4 v[70:71], v[62:65], off
	v_pk_add_f32 v[6:7], v[6:7], v[116:117]
	v_pk_add_f32 v[4:5], v[4:5], v[114:115]
	v_pk_add_f32 v[62:63], v[52:53], v[112:113]
	v_pk_add_f32 v[52:53], v[50:51], v[110:111]
	v_cvt_pk_bf16_f32 v50, v58, v59
	v_cvt_pk_bf16_f32 v51, v60, v61
	s_nop 0
	v_cvt_pk_bf16_f32 v52, v52, v53
	v_cvt_pk_bf16_f32 v53, v62, v63
	global_store_dwordx4 v[70:71], v[50:53], off offset:256
	s_nop 1
	v_add_u32_e32 v50, 0x90, v166
	v_mad_i64_i32 v[50:51], s[2:3], v50, s9, v[158:159]
	v_lshl_add_u64 v[50:51], v[50:51], 0, v[160:161]
	v_pk_add_f32 v[52:53], v[56:57], v[128:129]
	v_pk_add_f32 v[56:57], v[48:49], v[120:121]
	v_pk_add_f32 v[48:49], v[46:47], v[118:119]
	v_cvt_pk_bf16_f32 v46, v54, v55
	v_cvt_pk_bf16_f32 v47, v52, v53
	s_nop 0
	v_cvt_pk_bf16_f32 v48, v48, v49
	v_cvt_pk_bf16_f32 v49, v56, v57
	global_store_dwordx4 v[50:51], v[46:49], off
	s_nop 1
	v_pk_add_f32 v[46:47], v[36:37], v[112:113]
	v_pk_add_f32 v[36:37], v[34:35], v[110:111]
	v_cvt_pk_bf16_f32 v34, v42, v43
	v_cvt_pk_bf16_f32 v35, v44, v45
	s_nop 0
	v_cvt_pk_bf16_f32 v36, v36, v37
	v_cvt_pk_bf16_f32 v37, v46, v47
	global_store_dwordx4 v[50:51], v[34:37], off offset:256
	s_nop 1
	v_add_u32_e32 v34, 0xa0, v166
	v_mad_i64_i32 v[34:35], s[2:3], v34, s9, v[158:159]
	v_lshl_add_u64 v[34:35], v[34:35], 0, v[160:161]
	v_pk_add_f32 v[36:37], v[40:41], v[128:129]
	v_pk_add_f32 v[40:41], v[32:33], v[120:121]
	v_pk_add_f32 v[32:33], v[30:31], v[118:119]
	v_cvt_pk_bf16_f32 v30, v38, v39
	v_cvt_pk_bf16_f32 v31, v36, v37
	s_nop 0
	v_cvt_pk_bf16_f32 v32, v32, v33
	v_cvt_pk_bf16_f32 v33, v40, v41
	global_store_dwordx4 v[34:35], v[30:33], off
	s_nop 1
	v_pk_add_f32 v[30:31], v[20:21], v[112:113]
	v_pk_add_f32 v[20:21], v[18:19], v[110:111]
	v_cvt_pk_bf16_f32 v18, v26, v27
	v_cvt_pk_bf16_f32 v19, v28, v29
	s_nop 0
	v_cvt_pk_bf16_f32 v20, v20, v21
	v_cvt_pk_bf16_f32 v21, v30, v31
	global_store_dwordx4 v[34:35], v[18:21], off offset:256
	s_nop 1
	v_add_u32_e32 v18, 0xb0, v166
	v_mad_i64_i32 v[18:19], s[2:3], v18, s9, v[158:159]
	v_lshl_add_u64 v[18:19], v[18:19], 0, v[160:161]
	v_pk_add_f32 v[20:21], v[24:25], v[128:129]
	v_pk_add_f32 v[24:25], v[16:17], v[120:121]
	v_pk_add_f32 v[16:17], v[14:15], v[118:119]
	v_cvt_pk_bf16_f32 v14, v22, v23
	v_cvt_pk_bf16_f32 v15, v20, v21
	s_mov_b64 s[2:3], s[34:35]
	v_cvt_pk_bf16_f32 v16, v16, v17
	v_cvt_pk_bf16_f32 v17, v24, v25
	global_store_dwordx4 v[18:19], v[14:17], off
	s_nop 1
	v_pk_add_f32 v[14:15], v[2:3], v[112:113]
	v_pk_add_f32 v[2:3], v[0:1], v[110:111]
	v_cvt_pk_bf16_f32 v0, v4, v5
	v_cvt_pk_bf16_f32 v1, v6, v7
	s_nop 0
	v_cvt_pk_bf16_f32 v2, v2, v3
	v_cvt_pk_bf16_f32 v3, v14, v15
	global_store_dwordx4 v[18:19], v[0:3], off offset:256
	s_cbranch_vccz .LBB0_721
	s_waitcnt vmcnt(0)
	s_cmpk_gt_u32 s19, 0xff
	s_cbranch_scc1 .LBB0_728
	s_barrier
